# seams 9 10 11 turned into per-XCD counter barriers (row panels stay on one XCD: no L2 writeback, no cross-XCD step)
# speedup vs baseline: 1.0259x; 1.0070x over previous
; __device__ __forceinline__ unsigned xb_ld(unsigned* p)              { return __hip_atomic_load(p, __ATOMIC_RELAXED, __HIP_MEMORY_SCOPE_AGENT); }
; __device__ __forceinline__ unsigned xb_add(unsigned* p, unsigned v) { return __hip_atomic_fetch_add(p, v, __ATOMIC_RELAXED, __HIP_MEMORY_SCOPE_AGENT); }
; #define XB_SPIN(cond, bar) do { unsigned _sp = 0; while (cond) { __builtin_amdgcn_s_sleep(1); \
;     if ((++_sp & 255u) == 0u) { if (xb_ld(&(bar)[XB_TMO])) break; if (_sp > XB_SPIN_CAP) { atomicAdd(&(bar)[XB_TMO], 1u); break; } } } } while (0)
; #define SEAM(k) do { if (IN(k) && IN((k) + 1)) xcd_barrier(bar); } while (0)
; __device__ __forceinline__ void xcd_barrier(const XcdBarrier& b) {
;     asm volatile("s_waitcnt vmcnt(0)" ::: "memory");
;     __syncthreads();
;     if (threadIdx.x == 0) {
;         unsigned* bar = b.bar;
;         __builtin_amdgcn_s_waitcnt(0);
;         unsigned nloc = b.st[0], nx = b.st[1];
;         if (nloc == 0u) { xcd_barrier_complete(bar, b.x, nloc, nx); b.st[0] = nloc; b.st[1] = nx; }
;         const unsigned old = xb_add(&bar[XB_XSUB(b.x)], 1u);
;         const unsigned gen = old / nloc;
;         if (old + 1u == (gen + 1u) * nloc) {
;             __builtin_amdgcn_fence(__ATOMIC_RELEASE, "agent");
;             asm volatile("s_waitcnt vmcnt(0)" ::: "memory");
;             const unsigned og = xb_add(&bar[XB_TOP], 1u);
;             const unsigned tg = og / nx;
;             if (og + 1u == (tg + 1u) * nx) xb_add(&bar[XB_TOPGEN], 1u);
;             else XB_SPIN(xb_ld(&bar[XB_TOPGEN]) == tg, bar);
;             __builtin_amdgcn_fence(__ATOMIC_ACQUIRE, "agent");
;             xb_add(&bar[XB_XGEN(b.x)], 1u);
;             asm volatile("s_waitcnt vmcnt(0)" ::: "memory");
;         } else {
;             XB_SPIN(xb_ld(&bar[XB_XGEN(b.x)]) == gen, bar);
;             __builtin_amdgcn_fence(__ATOMIC_ACQUIRE, "agent");
;             asm volatile("s_waitcnt vmcnt(0)" ::: "memory");
;         }
;     }
;     __syncthreads();
; }
; __global__ void __launch_bounds__(NWAVES * 64, 2) mega_fwd(Args args) {
;     ...
;     SEAM(9);
;     if (IN(10)) { pg8::Gemm g{XB, W2gu, M, 2 * FF, DM, DM, DM, 0, 0, 1}; pg8::StaticOrder S; S.init(M, 2 * FF, 1, G, bx);
.LBB0_1235:
	s_cmp_gt_i32 s85, 10
	s_cselect_b64 s[2:3], -1, 0
	s_and_b64 s[0:1], s[0:1], s[2:3]
	s_andn2_b64 vcc, exec, s[0:1]
	s_cbranch_vccnz .LBB0_1289
	s_waitcnt vmcnt(0)
	s_waitcnt vmcnt(0) lgkmcnt(0)
	s_barrier
	s_and_saveexec_b64 s[0:1], s[74:75]
	s_cbranch_execz .LBB0_1288
	s_getreg_b32 s4, hwreg(HW_REG_XCC_ID, 0, 4)
	s_and_b32 s4, s4, 7
	s_lshl_b32 s4, s4, 8
	s_add_u32 s6, s66, 0xfd09000
	s_addc_u32 s7, s67, 0
	v_mov_b32_e32 v1, s4
	v_mov_b32_e32 v2, 1
	v_mov_b32_e32 v4, 0x20160
	ds_read_b32 v4, v4
	global_atomic_add v1, v2, s[6:7]
	s_waitcnt lgkmcnt(0)
	v_readfirstlane_b32 s5, v4
	s_mov_b32 s8, 0
	s_nop 2
	s_mul_i32 s5, s5, 1
.Lls9_spin:
	global_load_dword v3, v1, s[6:7] sc1
	s_waitcnt vmcnt(0)
	v_readfirstlane_b32 s9, v3
	s_nop 3
	s_cmp_ge_u32 s9, s5
	s_cbranch_scc1 .Lls9_ok
	s_sleep 1
	s_add_i32 s8, s8, 1
	s_cmp_lt_u32 s8, 0x20000
	s_cbranch_scc1 .Lls9_spin
.Lls9_ok:
	buffer_inv sc1
	s_waitcnt vmcnt(0)
.LBB0_1288:
	s_or_b64 exec, exec, s[0:1]
	s_waitcnt lgkmcnt(0)
	s_barrier

; __device__ __forceinline__ unsigned xb_ld(unsigned* p)              { return __hip_atomic_load(p, __ATOMIC_RELAXED, __HIP_MEMORY_SCOPE_AGENT); }
; __device__ __forceinline__ unsigned xb_add(unsigned* p, unsigned v) { return __hip_atomic_fetch_add(p, v, __ATOMIC_RELAXED, __HIP_MEMORY_SCOPE_AGENT); }
; #define XB_SPIN(cond, bar) do { unsigned _sp = 0; while (cond) { __builtin_amdgcn_s_sleep(1); \
;     if ((++_sp & 255u) == 0u) { if (xb_ld(&(bar)[XB_TMO])) break; if (_sp > XB_SPIN_CAP) { atomicAdd(&(bar)[XB_TMO], 1u); break; } } } } while (0)
; #define SEAM(k) do { if (IN(k) && IN((k) + 1)) xcd_barrier(bar); } while (0)
; __device__ __forceinline__ void xcd_barrier(const XcdBarrier& b) {
;     asm volatile("s_waitcnt vmcnt(0)" ::: "memory");
;     __syncthreads();
;     if (threadIdx.x == 0) {
;         unsigned* bar = b.bar;
;         __builtin_amdgcn_s_waitcnt(0);
;         unsigned nloc = b.st[0], nx = b.st[1];
;         if (nloc == 0u) { xcd_barrier_complete(bar, b.x, nloc, nx); b.st[0] = nloc; b.st[1] = nx; }
;         const unsigned old = xb_add(&bar[XB_XSUB(b.x)], 1u);
;         const unsigned gen = old / nloc;
;         if (old + 1u == (gen + 1u) * nloc) {
;             __builtin_amdgcn_fence(__ATOMIC_RELEASE, "agent");
;             asm volatile("s_waitcnt vmcnt(0)" ::: "memory");
;             const unsigned og = xb_add(&bar[XB_TOP], 1u);
;             const unsigned tg = og / nx;
;             if (og + 1u == (tg + 1u) * nx) xb_add(&bar[XB_TOPGEN], 1u);
;             else XB_SPIN(xb_ld(&bar[XB_TOPGEN]) == tg, bar);
;             __builtin_amdgcn_fence(__ATOMIC_ACQUIRE, "agent");
;             xb_add(&bar[XB_XGEN(b.x)], 1u);
;             asm volatile("s_waitcnt vmcnt(0)" ::: "memory");
;         } else {
;             XB_SPIN(xb_ld(&bar[XB_XGEN(b.x)]) == gen, bar);
;             __builtin_amdgcn_fence(__ATOMIC_ACQUIRE, "agent");
;             asm volatile("s_waitcnt vmcnt(0)" ::: "memory");
;         }
;     }
;     __syncthreads();
; }
; __global__ void __launch_bounds__(NWAVES * 64, 2) mega_fwd(Args args) {
;     ...
;     SEAM(10);
;     if (IN(11)) { pg8::Gemm g{ACT, W2d, M, DM, FF, 64, FF, 0, 0, 1, (size_t)256 * 64 * 2, (size_t)(FF / 64) * 256 * 64 * 2}; pg8::StaticOrder S; S.init(M, DM, 1, G, bx);
.LBB0_1327:
	s_cmp_gt_i32 s85, 11
	s_cselect_b64 s[2:3], -1, 0
	s_and_b64 s[0:1], s[0:1], s[2:3]
	v_readlane_b32 s48, v252, 22
	s_andn2_b64 vcc, exec, s[0:1]
	v_readlane_b32 s49, v252, 23
	s_cbranch_vccnz .LBB0_1381
	s_waitcnt vmcnt(0)
	s_waitcnt vmcnt(0) lgkmcnt(0)
	s_barrier
	s_and_saveexec_b64 s[0:1], s[74:75]
	s_cbranch_execz .LBB0_1380
	s_getreg_b32 s4, hwreg(HW_REG_XCC_ID, 0, 4)
	s_and_b32 s4, s4, 7
	s_lshl_b32 s4, s4, 8
	s_add_u32 s6, s66, 0xfd09000
	s_addc_u32 s7, s67, 0
	v_mov_b32_e32 v1, s4
	v_mov_b32_e32 v2, 1
	v_mov_b32_e32 v4, 0x20160
	ds_read_b32 v4, v4
	global_atomic_add v1, v2, s[6:7]
	s_waitcnt lgkmcnt(0)
	v_readfirstlane_b32 s5, v4
	s_mov_b32 s8, 0
	s_nop 2
	s_mul_i32 s5, s5, 2

; __device__ __forceinline__ unsigned xb_ld(unsigned* p)              { return __hip_atomic_load(p, __ATOMIC_RELAXED, __HIP_MEMORY_SCOPE_AGENT); }
; __device__ __forceinline__ unsigned xb_add(unsigned* p, unsigned v) { return __hip_atomic_fetch_add(p, v, __ATOMIC_RELAXED, __HIP_MEMORY_SCOPE_AGENT); }
; #define XB_SPIN(cond, bar) do { unsigned _sp = 0; while (cond) { __builtin_amdgcn_s_sleep(1); \
;     if ((++_sp & 255u) == 0u) { if (xb_ld(&(bar)[XB_TMO])) break; if (_sp > XB_SPIN_CAP) { atomicAdd(&(bar)[XB_TMO], 1u); break; } } } } while (0)
; __device__ __forceinline__ void xcd_barrier(const XcdBarrier& b) {
;     asm volatile("s_waitcnt vmcnt(0)" ::: "memory");
;     __syncthreads();
;     if (threadIdx.x == 0) {
;         unsigned* bar = b.bar;
;         __builtin_amdgcn_s_waitcnt(0);
;         unsigned nloc = b.st[0], nx = b.st[1];
;         if (nloc == 0u) { xcd_barrier_complete(bar, b.x, nloc, nx); b.st[0] = nloc; b.st[1] = nx; }
;         const unsigned old = xb_add(&bar[XB_XSUB(b.x)], 1u);
;         const unsigned gen = old / nloc;
;         if (old + 1u == (gen + 1u) * nloc) {
;             __builtin_amdgcn_fence(__ATOMIC_RELEASE, "agent");
;             asm volatile("s_waitcnt vmcnt(0)" ::: "memory");
;             const unsigned og = xb_add(&bar[XB_TOP], 1u);
;             const unsigned tg = og / nx;
;             if (og + 1u == (tg + 1u) * nx) xb_add(&bar[XB_TOPGEN], 1u);
;             else XB_SPIN(xb_ld(&bar[XB_TOPGEN]) == tg, bar);
;             __builtin_amdgcn_fence(__ATOMIC_ACQUIRE, "agent");
;             xb_add(&bar[XB_XGEN(b.x)], 1u);
;             asm volatile("s_waitcnt vmcnt(0)" ::: "memory");
;         } else {
;             XB_SPIN(xb_ld(&bar[XB_XGEN(b.x)]) == gen, bar);
;             __builtin_amdgcn_fence(__ATOMIC_ACQUIRE, "agent");
;             asm volatile("s_waitcnt vmcnt(0)" ::: "memory");
;         }
;     }
;     __syncthreads();
; }
.Lls10_ok:
	buffer_inv sc1
	s_waitcnt vmcnt(0)
.LBB0_1380:
	s_or_b64 exec, exec, s[0:1]
	s_waitcnt lgkmcnt(0)
	s_barrier

; __device__ __forceinline__ unsigned xb_ld(unsigned* p)              { return __hip_atomic_load(p, __ATOMIC_RELAXED, __HIP_MEMORY_SCOPE_AGENT); }
; __device__ __forceinline__ unsigned xb_add(unsigned* p, unsigned v) { return __hip_atomic_fetch_add(p, v, __ATOMIC_RELAXED, __HIP_MEMORY_SCOPE_AGENT); }
; #define XB_SPIN(cond, bar) do { unsigned _sp = 0; while (cond) { __builtin_amdgcn_s_sleep(1); \
;     if ((++_sp & 255u) == 0u) { if (xb_ld(&(bar)[XB_TMO])) break; if (_sp > XB_SPIN_CAP) { atomicAdd(&(bar)[XB_TMO], 1u); break; } } } } while (0)
; #define SEAM(k) do { if (IN(k) && IN((k) + 1)) xcd_barrier(bar); } while (0)
; __device__ __forceinline__ void xcd_barrier(const XcdBarrier& b) {
;     asm volatile("s_waitcnt vmcnt(0)" ::: "memory");
;     __syncthreads();
;     if (threadIdx.x == 0) {
;         unsigned* bar = b.bar;
;         __builtin_amdgcn_s_waitcnt(0);
;         unsigned nloc = b.st[0], nx = b.st[1];
;         if (nloc == 0u) { xcd_barrier_complete(bar, b.x, nloc, nx); b.st[0] = nloc; b.st[1] = nx; }
;         const unsigned old = xb_add(&bar[XB_XSUB(b.x)], 1u);
;         const unsigned gen = old / nloc;
;         if (old + 1u == (gen + 1u) * nloc) {
;             __builtin_amdgcn_fence(__ATOMIC_RELEASE, "agent");
;             asm volatile("s_waitcnt vmcnt(0)" ::: "memory");
;             const unsigned og = xb_add(&bar[XB_TOP], 1u);
;             const unsigned tg = og / nx;
;             if (og + 1u == (tg + 1u) * nx) xb_add(&bar[XB_TOPGEN], 1u);
;             else XB_SPIN(xb_ld(&bar[XB_TOPGEN]) == tg, bar);
;             __builtin_amdgcn_fence(__ATOMIC_ACQUIRE, "agent");
;             xb_add(&bar[XB_XGEN(b.x)], 1u);
;             asm volatile("s_waitcnt vmcnt(0)" ::: "memory");
;         } else {
;             XB_SPIN(xb_ld(&bar[XB_XGEN(b.x)]) == gen, bar);
;             __builtin_amdgcn_fence(__ATOMIC_ACQUIRE, "agent");
;             asm volatile("s_waitcnt vmcnt(0)" ::: "memory");
;         }
;     }
;     __syncthreads();
; }
; __global__ void __launch_bounds__(NWAVES * 64, 2) mega_fwd(Args args) {
;     ...
;     SEAM(11);
;     if (IN(12)) { pg8::StaticOrder S; S.init(M, DM, 1, G, bx);
.LBB0_1428:
	s_cmp_gt_i32 s85, 12
	s_cselect_b64 s[2:3], -1, 0
	s_and_b64 s[0:1], s[0:1], s[2:3]
	s_andn2_b64 vcc, exec, s[0:1]
	s_cbranch_vccnz .LBB0_1482
	s_waitcnt vmcnt(0)
	s_waitcnt vmcnt(0) lgkmcnt(0)
	s_barrier
	s_and_saveexec_b64 s[0:1], s[74:75]
	s_cbranch_execz .LBB0_1481
	s_getreg_b32 s4, hwreg(HW_REG_XCC_ID, 0, 4)
	s_and_b32 s4, s4, 7
	s_lshl_b32 s4, s4, 8
	s_add_u32 s6, s66, 0xfd09000
	s_addc_u32 s7, s67, 0
	v_mov_b32_e32 v1, s4
	v_mov_b32_e32 v2, 1
	v_mov_b32_e32 v4, 0x20160
	ds_read_b32 v4, v4
	global_atomic_add v1, v2, s[6:7]
	s_waitcnt lgkmcnt(0)
	v_readfirstlane_b32 s5, v4
	s_mov_b32 s8, 0
	s_nop 2
	s_mul_i32 s5, s5, 3

; __device__ __forceinline__ unsigned xb_ld(unsigned* p)              { return __hip_atomic_load(p, __ATOMIC_RELAXED, __HIP_MEMORY_SCOPE_AGENT); }
; __device__ __forceinline__ unsigned xb_add(unsigned* p, unsigned v) { return __hip_atomic_fetch_add(p, v, __ATOMIC_RELAXED, __HIP_MEMORY_SCOPE_AGENT); }
; #define XB_SPIN(cond, bar) do { unsigned _sp = 0; while (cond) { __builtin_amdgcn_s_sleep(1); \
;     if ((++_sp & 255u) == 0u) { if (xb_ld(&(bar)[XB_TMO])) break; if (_sp > XB_SPIN_CAP) { atomicAdd(&(bar)[XB_TMO], 1u); break; } } } } while (0)
; __device__ __forceinline__ void xcd_barrier(const XcdBarrier& b) {
;     asm volatile("s_waitcnt vmcnt(0)" ::: "memory");
;     __syncthreads();
;     if (threadIdx.x == 0) {
;         unsigned* bar = b.bar;
;         __builtin_amdgcn_s_waitcnt(0);
;         unsigned nloc = b.st[0], nx = b.st[1];
;         if (nloc == 0u) { xcd_barrier_complete(bar, b.x, nloc, nx); b.st[0] = nloc; b.st[1] = nx; }
;         const unsigned old = xb_add(&bar[XB_XSUB(b.x)], 1u);
;         const unsigned gen = old / nloc;
;         if (old + 1u == (gen + 1u) * nloc) {
;             __builtin_amdgcn_fence(__ATOMIC_RELEASE, "agent");
;             asm volatile("s_waitcnt vmcnt(0)" ::: "memory");
;             const unsigned og = xb_add(&bar[XB_TOP], 1u);
;             const unsigned tg = og / nx;
;             if (og + 1u == (tg + 1u) * nx) xb_add(&bar[XB_TOPGEN], 1u);
;             else XB_SPIN(xb_ld(&bar[XB_TOPGEN]) == tg, bar);
;             __builtin_amdgcn_fence(__ATOMIC_ACQUIRE, "agent");
;             xb_add(&bar[XB_XGEN(b.x)], 1u);
;             asm volatile("s_waitcnt vmcnt(0)" ::: "memory");
;         } else {
;             XB_SPIN(xb_ld(&bar[XB_XGEN(b.x)]) == gen, bar);
;             __builtin_amdgcn_fence(__ATOMIC_ACQUIRE, "agent");
;             asm volatile("s_waitcnt vmcnt(0)" ::: "memory");
;         }
;     }
;     __syncthreads();
; }
.Lls11_ok:
	buffer_inv sc1
	s_waitcnt vmcnt(0)
.LBB0_1481:
	s_or_b64 exec, exec, s[0:1]
	s_waitcnt lgkmcnt(0)
	s_barrier
